# prep: x to bf16 conversion done by workgroups 64..255 with all row loads issued up front (workgroups 0..63 carry the S5 tables); original loop kept as fallback for other grid sizes
# baseline (speedup 1.0000x reference)
.LBB0_961:
	s_or_b64 exec, exec, s[0:1]
	s_cmp_eq_u32 s18, 0x100
	s_cbranch_scc0 .Lxc_orig
	v_readlane_b32 s0, v254, 0
	s_nop 3
	s_cmp_lt_u32 s0, 64
	s_cbranch_scc1 .Lxc_done
	s_sub_i32 s2, s0, 64
	s_lshl_b32 s3, s2, 3
	v_and_b32_e32 v0, 63, v173
	v_lshrrev_b32_e32 v1, 6, v173
	v_add_u32_e32 v2, s3, v1
	v_mov_b32_e32 v3, 0
	v_readlane_b32 s20, v254, 19
	v_readlane_b32 s21, v254, 20
	v_readlane_b32 s6, v254, 40
	v_readlane_b32 s7, v254, 41
	v_lshlrev_b64 v[194:195], 12, v[2:3]
	v_lshlrev_b32_e32 v4, 5, v0
	v_mov_b32_e32 v5, 0
	v_lshl_add_u64 v[194:195], v[194:195], 0, v[4:5]
	v_lshl_add_u64 v[194:195], v[194:195], 0, s[20:21]
	s_mov_b64 s[4:5], 0x600000
	s_cmp_lt_u32 s2, 0x80
	s_cselect_b64 s[14:15], -1, 0
	global_load_dwordx4 v[16:19], v[194:195], off
	global_load_dwordx4 v[20:23], v[194:195], off offset:16
	global_load_dwordx4 v[24:27], v[194:195], off offset:2048
	global_load_dwordx4 v[28:31], v[194:195], off offset:2064
	v_lshl_add_u64 v[194:195], v[194:195], 0, s[4:5]
	global_load_dwordx4 v[32:35], v[194:195], off
	global_load_dwordx4 v[36:39], v[194:195], off offset:16
	global_load_dwordx4 v[40:43], v[194:195], off offset:2048
	global_load_dwordx4 v[44:47], v[194:195], off offset:2064
	v_lshl_add_u64 v[194:195], v[194:195], 0, s[4:5]
	global_load_dwordx4 v[48:51], v[194:195], off
	global_load_dwordx4 v[52:55], v[194:195], off offset:16
	global_load_dwordx4 v[56:59], v[194:195], off offset:2048
	global_load_dwordx4 v[60:63], v[194:195], off offset:2064
	v_lshl_add_u64 v[194:195], v[194:195], 0, s[4:5]
	global_load_dwordx4 v[64:67], v[194:195], off
	global_load_dwordx4 v[68:71], v[194:195], off offset:16
	global_load_dwordx4 v[72:75], v[194:195], off offset:2048
	global_load_dwordx4 v[76:79], v[194:195], off offset:2064
	v_lshl_add_u64 v[194:195], v[194:195], 0, s[4:5]
	global_load_dwordx4 v[80:83], v[194:195], off
	global_load_dwordx4 v[84:87], v[194:195], off offset:16
	global_load_dwordx4 v[88:91], v[194:195], off offset:2048
	global_load_dwordx4 v[92:95], v[194:195], off offset:2064
	v_lshl_add_u64 v[194:195], v[194:195], 0, s[4:5]
	global_load_dwordx4 v[96:99], v[194:195], off
	global_load_dwordx4 v[100:103], v[194:195], off offset:16
	global_load_dwordx4 v[104:107], v[194:195], off offset:2048
	global_load_dwordx4 v[108:111], v[194:195], off offset:2064
	v_lshl_add_u64 v[194:195], v[194:195], 0, s[4:5]
	global_load_dwordx4 v[112:115], v[194:195], off
	global_load_dwordx4 v[116:119], v[194:195], off offset:16
	global_load_dwordx4 v[120:123], v[194:195], off offset:2048
	global_load_dwordx4 v[124:127], v[194:195], off offset:2064
	v_lshl_add_u64 v[194:195], v[194:195], 0, s[4:5]
	global_load_dwordx4 v[128:131], v[194:195], off
	global_load_dwordx4 v[132:135], v[194:195], off offset:16
	global_load_dwordx4 v[136:139], v[194:195], off offset:2048
	global_load_dwordx4 v[140:143], v[194:195], off offset:2064
	v_lshl_add_u64 v[194:195], v[194:195], 0, s[4:5]
	global_load_dwordx4 v[144:147], v[194:195], off
	global_load_dwordx4 v[148:151], v[194:195], off offset:16
	global_load_dwordx4 v[152:155], v[194:195], off offset:2048
	global_load_dwordx4 v[156:159], v[194:195], off offset:2064
	v_lshl_add_u64 v[194:195], v[194:195], 0, s[4:5]
	global_load_dwordx4 v[176:179], v[194:195], off
	global_load_dwordx4 v[180:183], v[194:195], off offset:16
	global_load_dwordx4 v[184:187], v[194:195], off offset:2048
	global_load_dwordx4 v[188:191], v[194:195], off offset:2064
	v_lshl_add_u64 v[194:195], v[194:195], 0, s[4:5]
	s_and_b64 vcc, exec, s[14:15]
	s_cbranch_vccz .Lxc_no10
	global_load_dwordx4 v[216:219], v[194:195], off
	global_load_dwordx4 v[220:223], v[194:195], off offset:16
	global_load_dwordx4 v[224:227], v[194:195], off offset:2048
	global_load_dwordx4 v[228:231], v[194:195], off offset:2064
.Lxc_no10:
	s_add_u32 s8, s6, 0xb400000
	s_addc_u32 s9, s7, 0
	s_add_u32 s10, s6, 0xd400000
	s_addc_u32 s11, s7, 0
	v_lshlrev_b64 v[196:197], 11, v[2:3]
	v_lshlrev_b32_e32 v4, 4, v0
	v_lshl_add_u64 v[196:197], v[196:197], 0, v[4:5]
	v_lshl_add_u64 v[196:197], v[196:197], 0, s[8:9]
	v_lshlrev_b64 v[198:199], 6, v[2:3]
	v_lshlrev_b32_e32 v4, 2, v0
	v_lshl_add_u64 v[198:199], v[198:199], 0, v[4:5]
	v_lshl_add_u64 v[198:199], v[198:199], 0, s[10:11]
	s_mov_b64 s[8:9], 0x300000
	s_mov_b64 s[10:11], 0x18000
	v_xor_b32_e32 v200, 32, v0
	v_xor_b32_e32 v201, 16, v0
	v_xor_b32_e32 v202, 8, v0
	v_xor_b32_e32 v203, 4, v0
	v_xor_b32_e32 v204, 2, v0
	v_xor_b32_e32 v205, 1, v0
	v_lshlrev_b32_e32 v200, 2, v200
	v_lshlrev_b32_e32 v201, 2, v201
	v_lshlrev_b32_e32 v202, 2, v202
	v_lshlrev_b32_e32 v203, 2, v203
	v_lshlrev_b32_e32 v204, 2, v204
	v_lshlrev_b32_e32 v205, 2, v205
	v_cmp_eq_u32_e64 s[12:13], 0, v0
	s_waitcnt vmcnt(36)
	v_cvt_pk_bf16_f32 v4, v16, v17
	v_cvt_pk_bf16_f32 v5, v18, v19
	v_cvt_pk_bf16_f32 v6, v20, v21
	v_cvt_pk_bf16_f32 v7, v22, v23
	v_cvt_pk_bf16_f32 v8, v24, v25
	v_cvt_pk_bf16_f32 v9, v26, v27
	v_cvt_pk_bf16_f32 v10, v28, v29
	v_cvt_pk_bf16_f32 v11, v30, v31
	global_store_dwordx4 v[196:197], v[4:7], off
	global_store_dwordx4 v[196:197], v[8:11], off offset:1024
	v_lshl_add_u64 v[196:197], v[196:197], 0, s[8:9]
	v_lshlrev_b32_e32 v16, 16, v4
	v_and_b32_e32 v17, 0xffff0000, v4
	v_lshlrev_b32_e32 v18, 16, v5
	v_and_b32_e32 v19, 0xffff0000, v5
	v_lshlrev_b32_e32 v20, 16, v6
	v_and_b32_e32 v21, 0xffff0000, v6
	v_lshlrev_b32_e32 v22, 16, v7
	v_and_b32_e32 v23, 0xffff0000, v7
	v_lshlrev_b32_e32 v24, 16, v8
	v_and_b32_e32 v25, 0xffff0000, v8
	v_lshlrev_b32_e32 v26, 16, v9
	v_and_b32_e32 v27, 0xffff0000, v9
	v_lshlrev_b32_e32 v28, 16, v10
	v_and_b32_e32 v29, 0xffff0000, v10
	v_lshlrev_b32_e32 v30, 16, v11
	v_and_b32_e32 v31, 0xffff0000, v11
	v_mul_f32_e32 v12, v17, v17
	v_fmac_f32_e32 v12, v16, v16
	v_fmac_f32_e32 v12, v18, v18
	v_fmac_f32_e32 v12, v19, v19
	v_fmac_f32_e32 v12, v20, v20
	v_fmac_f32_e32 v12, v21, v21
	v_fmac_f32_e32 v12, v22, v22
	v_fmac_f32_e32 v12, v23, v23
	v_fmac_f32_e32 v12, v24, v24
	v_fmac_f32_e32 v12, v25, v25
	v_fmac_f32_e32 v12, v26, v26
	v_fmac_f32_e32 v12, v27, v27
	v_fmac_f32_e32 v12, v28, v28
	v_fmac_f32_e32 v12, v29, v29
	v_fmac_f32_e32 v12, v30, v30
	v_fmac_f32_e32 v12, v31, v31
	s_waitcnt vmcnt(34)
	v_cvt_pk_bf16_f32 v206, v32, v33
	v_cvt_pk_bf16_f32 v207, v34, v35
	v_cvt_pk_bf16_f32 v208, v36, v37
	v_cvt_pk_bf16_f32 v209, v38, v39
	v_cvt_pk_bf16_f32 v210, v40, v41
	v_cvt_pk_bf16_f32 v211, v42, v43
	v_cvt_pk_bf16_f32 v212, v44, v45
	v_cvt_pk_bf16_f32 v213, v46, v47
	global_store_dwordx4 v[196:197], v[206:209], off
	global_store_dwordx4 v[196:197], v[210:213], off offset:1024
	v_lshl_add_u64 v[196:197], v[196:197], 0, s[8:9]
	v_lshlrev_b32_e32 v32, 16, v206
	v_and_b32_e32 v33, 0xffff0000, v206
	v_lshlrev_b32_e32 v34, 16, v207
	v_and_b32_e32 v35, 0xffff0000, v207
	v_lshlrev_b32_e32 v36, 16, v208
	v_and_b32_e32 v37, 0xffff0000, v208
	v_lshlrev_b32_e32 v38, 16, v209
	v_and_b32_e32 v39, 0xffff0000, v209
	v_lshlrev_b32_e32 v40, 16, v210
	v_and_b32_e32 v41, 0xffff0000, v210
	v_lshlrev_b32_e32 v42, 16, v211
	v_and_b32_e32 v43, 0xffff0000, v211
	v_lshlrev_b32_e32 v44, 16, v212
	v_and_b32_e32 v45, 0xffff0000, v212
	v_lshlrev_b32_e32 v46, 16, v213
	v_and_b32_e32 v47, 0xffff0000, v213
	v_mul_f32_e32 v214, v33, v33
	v_fmac_f32_e32 v214, v32, v32
	v_fmac_f32_e32 v214, v34, v34
	v_fmac_f32_e32 v214, v35, v35
	v_fmac_f32_e32 v214, v36, v36
	v_fmac_f32_e32 v214, v37, v37
	v_fmac_f32_e32 v214, v38, v38
	v_fmac_f32_e32 v214, v39, v39
	v_fmac_f32_e32 v214, v40, v40
	v_fmac_f32_e32 v214, v41, v41
	v_fmac_f32_e32 v214, v42, v42
	v_fmac_f32_e32 v214, v43, v43
	v_fmac_f32_e32 v214, v44, v44
	v_fmac_f32_e32 v214, v45, v45
	v_fmac_f32_e32 v214, v46, v46
	v_fmac_f32_e32 v214, v47, v47
	ds_bpermute_b32 v13, v200, v12
	ds_bpermute_b32 v215, v200, v214
	s_waitcnt lgkmcnt(0)
	v_add_f32_e32 v12, v12, v13
	v_add_f32_e32 v214, v214, v215
	ds_bpermute_b32 v13, v201, v12
	ds_bpermute_b32 v215, v201, v214
	s_waitcnt lgkmcnt(0)
	v_add_f32_e32 v12, v12, v13
	v_add_f32_e32 v214, v214, v215
	ds_bpermute_b32 v13, v202, v12
	ds_bpermute_b32 v215, v202, v214
	s_waitcnt lgkmcnt(0)
	v_add_f32_e32 v12, v12, v13
	v_add_f32_e32 v214, v214, v215
	ds_bpermute_b32 v13, v203, v12
	ds_bpermute_b32 v215, v203, v214
	s_waitcnt lgkmcnt(0)
	v_add_f32_e32 v12, v12, v13
	v_add_f32_e32 v214, v214, v215
	ds_bpermute_b32 v13, v204, v12
	ds_bpermute_b32 v215, v204, v214
	s_waitcnt lgkmcnt(0)
	v_add_f32_e32 v12, v12, v13
	v_add_f32_e32 v214, v214, v215
	ds_bpermute_b32 v13, v205, v12
	ds_bpermute_b32 v215, v205, v214
	s_waitcnt lgkmcnt(0)
	v_add_f32_e32 v12, v12, v13
	v_add_f32_e32 v214, v214, v215
	v_cndmask_b32_e64 v13, 0, v12, s[12:13]
	v_cndmask_b32_e64 v215, 0, v214, s[12:13]
	s_mov_b64 exec, 0xffff
	global_store_dword v[198:199], v13, off
	s_mov_b64 exec, -1
	v_lshl_add_u64 v[198:199], v[198:199], 0, s[10:11]
	s_mov_b64 exec, 0xffff
	global_store_dword v[198:199], v215, off
	s_mov_b64 exec, -1
	v_lshl_add_u64 v[198:199], v[198:199], 0, s[10:11]
	s_waitcnt vmcnt(34)
	v_cvt_pk_bf16_f32 v4, v48, v49
	v_cvt_pk_bf16_f32 v5, v50, v51
	v_cvt_pk_bf16_f32 v6, v52, v53
	v_cvt_pk_bf16_f32 v7, v54, v55
	v_cvt_pk_bf16_f32 v8, v56, v57
	v_cvt_pk_bf16_f32 v9, v58, v59
	v_cvt_pk_bf16_f32 v10, v60, v61
	v_cvt_pk_bf16_f32 v11, v62, v63
	global_store_dwordx4 v[196:197], v[4:7], off
	global_store_dwordx4 v[196:197], v[8:11], off offset:1024
	v_lshl_add_u64 v[196:197], v[196:197], 0, s[8:9]
	v_lshlrev_b32_e32 v48, 16, v4
	v_and_b32_e32 v49, 0xffff0000, v4
	v_lshlrev_b32_e32 v50, 16, v5
	v_and_b32_e32 v51, 0xffff0000, v5
	v_lshlrev_b32_e32 v52, 16, v6
	v_and_b32_e32 v53, 0xffff0000, v6
	v_lshlrev_b32_e32 v54, 16, v7
	v_and_b32_e32 v55, 0xffff0000, v7
	v_lshlrev_b32_e32 v56, 16, v8
	v_and_b32_e32 v57, 0xffff0000, v8
	v_lshlrev_b32_e32 v58, 16, v9
	v_and_b32_e32 v59, 0xffff0000, v9
	v_lshlrev_b32_e32 v60, 16, v10
	v_and_b32_e32 v61, 0xffff0000, v10
	v_lshlrev_b32_e32 v62, 16, v11
	v_and_b32_e32 v63, 0xffff0000, v11
	v_mul_f32_e32 v12, v49, v49
	v_fmac_f32_e32 v12, v48, v48
	v_fmac_f32_e32 v12, v50, v50
	v_fmac_f32_e32 v12, v51, v51
	v_fmac_f32_e32 v12, v52, v52
	v_fmac_f32_e32 v12, v53, v53
	v_fmac_f32_e32 v12, v54, v54
	v_fmac_f32_e32 v12, v55, v55
	v_fmac_f32_e32 v12, v56, v56
	v_fmac_f32_e32 v12, v57, v57
	v_fmac_f32_e32 v12, v58, v58
	v_fmac_f32_e32 v12, v59, v59
	v_fmac_f32_e32 v12, v60, v60
	v_fmac_f32_e32 v12, v61, v61
	v_fmac_f32_e32 v12, v62, v62
	v_fmac_f32_e32 v12, v63, v63
	s_waitcnt vmcnt(32)
	v_cvt_pk_bf16_f32 v206, v64, v65
	v_cvt_pk_bf16_f32 v207, v66, v67
	v_cvt_pk_bf16_f32 v208, v68, v69
	v_cvt_pk_bf16_f32 v209, v70, v71
	v_cvt_pk_bf16_f32 v210, v72, v73
	v_cvt_pk_bf16_f32 v211, v74, v75
	v_cvt_pk_bf16_f32 v212, v76, v77
	v_cvt_pk_bf16_f32 v213, v78, v79
	global_store_dwordx4 v[196:197], v[206:209], off
	global_store_dwordx4 v[196:197], v[210:213], off offset:1024
	v_lshl_add_u64 v[196:197], v[196:197], 0, s[8:9]
	v_lshlrev_b32_e32 v64, 16, v206
	v_and_b32_e32 v65, 0xffff0000, v206
	v_lshlrev_b32_e32 v66, 16, v207
	v_and_b32_e32 v67, 0xffff0000, v207
	v_lshlrev_b32_e32 v68, 16, v208
	v_and_b32_e32 v69, 0xffff0000, v208
	v_lshlrev_b32_e32 v70, 16, v209
	v_and_b32_e32 v71, 0xffff0000, v209
	v_lshlrev_b32_e32 v72, 16, v210
	v_and_b32_e32 v73, 0xffff0000, v210
	v_lshlrev_b32_e32 v74, 16, v211
	v_and_b32_e32 v75, 0xffff0000, v211
	v_lshlrev_b32_e32 v76, 16, v212
	v_and_b32_e32 v77, 0xffff0000, v212
	v_lshlrev_b32_e32 v78, 16, v213
	v_and_b32_e32 v79, 0xffff0000, v213
	v_mul_f32_e32 v214, v65, v65
	v_fmac_f32_e32 v214, v64, v64
	v_fmac_f32_e32 v214, v66, v66
	v_fmac_f32_e32 v214, v67, v67
	v_fmac_f32_e32 v214, v68, v68
	v_fmac_f32_e32 v214, v69, v69
	v_fmac_f32_e32 v214, v70, v70
	v_fmac_f32_e32 v214, v71, v71
	v_fmac_f32_e32 v214, v72, v72
	v_fmac_f32_e32 v214, v73, v73
	v_fmac_f32_e32 v214, v74, v74
	v_fmac_f32_e32 v214, v75, v75
	v_fmac_f32_e32 v214, v76, v76
	v_fmac_f32_e32 v214, v77, v77
	v_fmac_f32_e32 v214, v78, v78
	v_fmac_f32_e32 v214, v79, v79
	ds_bpermute_b32 v13, v200, v12
	ds_bpermute_b32 v215, v200, v214
	s_waitcnt lgkmcnt(0)
	v_add_f32_e32 v12, v12, v13
	v_add_f32_e32 v214, v214, v215
	ds_bpermute_b32 v13, v201, v12
	ds_bpermute_b32 v215, v201, v214
	s_waitcnt lgkmcnt(0)
	v_add_f32_e32 v12, v12, v13
	v_add_f32_e32 v214, v214, v215
	ds_bpermute_b32 v13, v202, v12
	ds_bpermute_b32 v215, v202, v214
	s_waitcnt lgkmcnt(0)
	v_add_f32_e32 v12, v12, v13
	v_add_f32_e32 v214, v214, v215
	ds_bpermute_b32 v13, v203, v12
	ds_bpermute_b32 v215, v203, v214
	s_waitcnt lgkmcnt(0)
	v_add_f32_e32 v12, v12, v13
	v_add_f32_e32 v214, v214, v215
	ds_bpermute_b32 v13, v204, v12
	ds_bpermute_b32 v215, v204, v214
	s_waitcnt lgkmcnt(0)
	v_add_f32_e32 v12, v12, v13
	v_add_f32_e32 v214, v214, v215
	ds_bpermute_b32 v13, v205, v12
	ds_bpermute_b32 v215, v205, v214
	s_waitcnt lgkmcnt(0)
	v_add_f32_e32 v12, v12, v13
	v_add_f32_e32 v214, v214, v215
	v_cndmask_b32_e64 v13, 0, v12, s[12:13]
	v_cndmask_b32_e64 v215, 0, v214, s[12:13]
	s_mov_b64 exec, 0xffff
	global_store_dword v[198:199], v13, off
	s_mov_b64 exec, -1
	v_lshl_add_u64 v[198:199], v[198:199], 0, s[10:11]
	s_mov_b64 exec, 0xffff
	global_store_dword v[198:199], v215, off
	s_mov_b64 exec, -1
	v_lshl_add_u64 v[198:199], v[198:199], 0, s[10:11]
	s_waitcnt vmcnt(32)
	v_cvt_pk_bf16_f32 v4, v80, v81
	v_cvt_pk_bf16_f32 v5, v82, v83
	v_cvt_pk_bf16_f32 v6, v84, v85
	v_cvt_pk_bf16_f32 v7, v86, v87
	v_cvt_pk_bf16_f32 v8, v88, v89
	v_cvt_pk_bf16_f32 v9, v90, v91
	v_cvt_pk_bf16_f32 v10, v92, v93
	v_cvt_pk_bf16_f32 v11, v94, v95
	global_store_dwordx4 v[196:197], v[4:7], off
	global_store_dwordx4 v[196:197], v[8:11], off offset:1024
	v_lshl_add_u64 v[196:197], v[196:197], 0, s[8:9]
	v_lshlrev_b32_e32 v80, 16, v4
	v_and_b32_e32 v81, 0xffff0000, v4
	v_lshlrev_b32_e32 v82, 16, v5
	v_and_b32_e32 v83, 0xffff0000, v5
	v_lshlrev_b32_e32 v84, 16, v6
	v_and_b32_e32 v85, 0xffff0000, v6
	v_lshlrev_b32_e32 v86, 16, v7
	v_and_b32_e32 v87, 0xffff0000, v7
	v_lshlrev_b32_e32 v88, 16, v8
	v_and_b32_e32 v89, 0xffff0000, v8
	v_lshlrev_b32_e32 v90, 16, v9
	v_and_b32_e32 v91, 0xffff0000, v9
	v_lshlrev_b32_e32 v92, 16, v10
	v_and_b32_e32 v93, 0xffff0000, v10
	v_lshlrev_b32_e32 v94, 16, v11
	v_and_b32_e32 v95, 0xffff0000, v11
	v_mul_f32_e32 v12, v81, v81
	v_fmac_f32_e32 v12, v80, v80
	v_fmac_f32_e32 v12, v82, v82
	v_fmac_f32_e32 v12, v83, v83
	v_fmac_f32_e32 v12, v84, v84
	v_fmac_f32_e32 v12, v85, v85
	v_fmac_f32_e32 v12, v86, v86
	v_fmac_f32_e32 v12, v87, v87
	v_fmac_f32_e32 v12, v88, v88
	v_fmac_f32_e32 v12, v89, v89
	v_fmac_f32_e32 v12, v90, v90
	v_fmac_f32_e32 v12, v91, v91
	v_fmac_f32_e32 v12, v92, v92
	v_fmac_f32_e32 v12, v93, v93
	v_fmac_f32_e32 v12, v94, v94
	v_fmac_f32_e32 v12, v95, v95
	s_waitcnt vmcnt(30)
	v_cvt_pk_bf16_f32 v206, v96, v97
	v_cvt_pk_bf16_f32 v207, v98, v99
	v_cvt_pk_bf16_f32 v208, v100, v101
	v_cvt_pk_bf16_f32 v209, v102, v103
	v_cvt_pk_bf16_f32 v210, v104, v105
	v_cvt_pk_bf16_f32 v211, v106, v107
	v_cvt_pk_bf16_f32 v212, v108, v109
	v_cvt_pk_bf16_f32 v213, v110, v111
	global_store_dwordx4 v[196:197], v[206:209], off
	global_store_dwordx4 v[196:197], v[210:213], off offset:1024
	v_lshl_add_u64 v[196:197], v[196:197], 0, s[8:9]
	v_lshlrev_b32_e32 v96, 16, v206
	v_and_b32_e32 v97, 0xffff0000, v206
	v_lshlrev_b32_e32 v98, 16, v207
	v_and_b32_e32 v99, 0xffff0000, v207
	v_lshlrev_b32_e32 v100, 16, v208
	v_and_b32_e32 v101, 0xffff0000, v208
	v_lshlrev_b32_e32 v102, 16, v209
	v_and_b32_e32 v103, 0xffff0000, v209
	v_lshlrev_b32_e32 v104, 16, v210
	v_and_b32_e32 v105, 0xffff0000, v210
	v_lshlrev_b32_e32 v106, 16, v211
	v_and_b32_e32 v107, 0xffff0000, v211
	v_lshlrev_b32_e32 v108, 16, v212
	v_and_b32_e32 v109, 0xffff0000, v212
	v_lshlrev_b32_e32 v110, 16, v213
	v_and_b32_e32 v111, 0xffff0000, v213
	v_mul_f32_e32 v214, v97, v97
	v_fmac_f32_e32 v214, v96, v96
	v_fmac_f32_e32 v214, v98, v98
	v_fmac_f32_e32 v214, v99, v99
	v_fmac_f32_e32 v214, v100, v100
	v_fmac_f32_e32 v214, v101, v101
	v_fmac_f32_e32 v214, v102, v102
	v_fmac_f32_e32 v214, v103, v103
	v_fmac_f32_e32 v214, v104, v104
	v_fmac_f32_e32 v214, v105, v105
	v_fmac_f32_e32 v214, v106, v106
	v_fmac_f32_e32 v214, v107, v107
	v_fmac_f32_e32 v214, v108, v108
	v_fmac_f32_e32 v214, v109, v109
	v_fmac_f32_e32 v214, v110, v110
	v_fmac_f32_e32 v214, v111, v111
	ds_bpermute_b32 v13, v200, v12
	ds_bpermute_b32 v215, v200, v214
	s_waitcnt lgkmcnt(0)
	v_add_f32_e32 v12, v12, v13
	v_add_f32_e32 v214, v214, v215
	ds_bpermute_b32 v13, v201, v12
	ds_bpermute_b32 v215, v201, v214
	s_waitcnt lgkmcnt(0)
	v_add_f32_e32 v12, v12, v13
	v_add_f32_e32 v214, v214, v215
	ds_bpermute_b32 v13, v202, v12
	ds_bpermute_b32 v215, v202, v214
	s_waitcnt lgkmcnt(0)
	v_add_f32_e32 v12, v12, v13
	v_add_f32_e32 v214, v214, v215
	ds_bpermute_b32 v13, v203, v12
	ds_bpermute_b32 v215, v203, v214
	s_waitcnt lgkmcnt(0)
	v_add_f32_e32 v12, v12, v13
	v_add_f32_e32 v214, v214, v215
	ds_bpermute_b32 v13, v204, v12
	ds_bpermute_b32 v215, v204, v214
	s_waitcnt lgkmcnt(0)
	v_add_f32_e32 v12, v12, v13
	v_add_f32_e32 v214, v214, v215
	ds_bpermute_b32 v13, v205, v12
	ds_bpermute_b32 v215, v205, v214
	s_waitcnt lgkmcnt(0)
	v_add_f32_e32 v12, v12, v13
	v_add_f32_e32 v214, v214, v215
	v_cndmask_b32_e64 v13, 0, v12, s[12:13]
	v_cndmask_b32_e64 v215, 0, v214, s[12:13]
	s_mov_b64 exec, 0xffff
	global_store_dword v[198:199], v13, off
	s_mov_b64 exec, -1
	v_lshl_add_u64 v[198:199], v[198:199], 0, s[10:11]
	s_mov_b64 exec, 0xffff
	global_store_dword v[198:199], v215, off
	s_mov_b64 exec, -1
	v_lshl_add_u64 v[198:199], v[198:199], 0, s[10:11]
	s_waitcnt vmcnt(30)
	v_cvt_pk_bf16_f32 v4, v112, v113
	v_cvt_pk_bf16_f32 v5, v114, v115
	v_cvt_pk_bf16_f32 v6, v116, v117
	v_cvt_pk_bf16_f32 v7, v118, v119
	v_cvt_pk_bf16_f32 v8, v120, v121
	v_cvt_pk_bf16_f32 v9, v122, v123
	v_cvt_pk_bf16_f32 v10, v124, v125
	v_cvt_pk_bf16_f32 v11, v126, v127
	global_store_dwordx4 v[196:197], v[4:7], off
	global_store_dwordx4 v[196:197], v[8:11], off offset:1024
	v_lshl_add_u64 v[196:197], v[196:197], 0, s[8:9]
	v_lshlrev_b32_e32 v112, 16, v4
	v_and_b32_e32 v113, 0xffff0000, v4
	v_lshlrev_b32_e32 v114, 16, v5
	v_and_b32_e32 v115, 0xffff0000, v5
	v_lshlrev_b32_e32 v116, 16, v6
	v_and_b32_e32 v117, 0xffff0000, v6
	v_lshlrev_b32_e32 v118, 16, v7
	v_and_b32_e32 v119, 0xffff0000, v7
	v_lshlrev_b32_e32 v120, 16, v8
	v_and_b32_e32 v121, 0xffff0000, v8
	v_lshlrev_b32_e32 v122, 16, v9
	v_and_b32_e32 v123, 0xffff0000, v9
	v_lshlrev_b32_e32 v124, 16, v10
	v_and_b32_e32 v125, 0xffff0000, v10
	v_lshlrev_b32_e32 v126, 16, v11
	v_and_b32_e32 v127, 0xffff0000, v11
	v_mul_f32_e32 v12, v113, v113
	v_fmac_f32_e32 v12, v112, v112
	v_fmac_f32_e32 v12, v114, v114
	v_fmac_f32_e32 v12, v115, v115
	v_fmac_f32_e32 v12, v116, v116
	v_fmac_f32_e32 v12, v117, v117
	v_fmac_f32_e32 v12, v118, v118
	v_fmac_f32_e32 v12, v119, v119
	v_fmac_f32_e32 v12, v120, v120
	v_fmac_f32_e32 v12, v121, v121
	v_fmac_f32_e32 v12, v122, v122
	v_fmac_f32_e32 v12, v123, v123
	v_fmac_f32_e32 v12, v124, v124
	v_fmac_f32_e32 v12, v125, v125
	v_fmac_f32_e32 v12, v126, v126
	v_fmac_f32_e32 v12, v127, v127
	s_waitcnt vmcnt(28)
	v_cvt_pk_bf16_f32 v206, v128, v129
	v_cvt_pk_bf16_f32 v207, v130, v131
	v_cvt_pk_bf16_f32 v208, v132, v133
	v_cvt_pk_bf16_f32 v209, v134, v135
	v_cvt_pk_bf16_f32 v210, v136, v137
	v_cvt_pk_bf16_f32 v211, v138, v139
	v_cvt_pk_bf16_f32 v212, v140, v141
	v_cvt_pk_bf16_f32 v213, v142, v143
	global_store_dwordx4 v[196:197], v[206:209], off
	global_store_dwordx4 v[196:197], v[210:213], off offset:1024
	v_lshl_add_u64 v[196:197], v[196:197], 0, s[8:9]
	v_lshlrev_b32_e32 v128, 16, v206
	v_and_b32_e32 v129, 0xffff0000, v206
	v_lshlrev_b32_e32 v130, 16, v207
	v_and_b32_e32 v131, 0xffff0000, v207
	v_lshlrev_b32_e32 v132, 16, v208
	v_and_b32_e32 v133, 0xffff0000, v208
	v_lshlrev_b32_e32 v134, 16, v209
	v_and_b32_e32 v135, 0xffff0000, v209
	v_lshlrev_b32_e32 v136, 16, v210
	v_and_b32_e32 v137, 0xffff0000, v210
	v_lshlrev_b32_e32 v138, 16, v211
	v_and_b32_e32 v139, 0xffff0000, v211
	v_lshlrev_b32_e32 v140, 16, v212
	v_and_b32_e32 v141, 0xffff0000, v212
	v_lshlrev_b32_e32 v142, 16, v213
	v_and_b32_e32 v143, 0xffff0000, v213
	v_mul_f32_e32 v214, v129, v129
	v_fmac_f32_e32 v214, v128, v128
	v_fmac_f32_e32 v214, v130, v130
	v_fmac_f32_e32 v214, v131, v131
	v_fmac_f32_e32 v214, v132, v132
	v_fmac_f32_e32 v214, v133, v133
	v_fmac_f32_e32 v214, v134, v134
	v_fmac_f32_e32 v214, v135, v135
	v_fmac_f32_e32 v214, v136, v136
	v_fmac_f32_e32 v214, v137, v137
	v_fmac_f32_e32 v214, v138, v138
	v_fmac_f32_e32 v214, v139, v139
	v_fmac_f32_e32 v214, v140, v140
	v_fmac_f32_e32 v214, v141, v141
	v_fmac_f32_e32 v214, v142, v142
	v_fmac_f32_e32 v214, v143, v143
	ds_bpermute_b32 v13, v200, v12
	ds_bpermute_b32 v215, v200, v214
	s_waitcnt lgkmcnt(0)
	v_add_f32_e32 v12, v12, v13
	v_add_f32_e32 v214, v214, v215
	ds_bpermute_b32 v13, v201, v12
	ds_bpermute_b32 v215, v201, v214
	s_waitcnt lgkmcnt(0)
	v_add_f32_e32 v12, v12, v13
	v_add_f32_e32 v214, v214, v215
	ds_bpermute_b32 v13, v202, v12
	ds_bpermute_b32 v215, v202, v214
	s_waitcnt lgkmcnt(0)
	v_add_f32_e32 v12, v12, v13
	v_add_f32_e32 v214, v214, v215
	ds_bpermute_b32 v13, v203, v12
	ds_bpermute_b32 v215, v203, v214
	s_waitcnt lgkmcnt(0)
	v_add_f32_e32 v12, v12, v13
	v_add_f32_e32 v214, v214, v215
	ds_bpermute_b32 v13, v204, v12
	ds_bpermute_b32 v215, v204, v214
	s_waitcnt lgkmcnt(0)
	v_add_f32_e32 v12, v12, v13
	v_add_f32_e32 v214, v214, v215
	ds_bpermute_b32 v13, v205, v12
	ds_bpermute_b32 v215, v205, v214
	s_waitcnt lgkmcnt(0)
	v_add_f32_e32 v12, v12, v13
	v_add_f32_e32 v214, v214, v215
	v_cndmask_b32_e64 v13, 0, v12, s[12:13]
	v_cndmask_b32_e64 v215, 0, v214, s[12:13]
	s_mov_b64 exec, 0xffff
	global_store_dword v[198:199], v13, off
	s_mov_b64 exec, -1
	v_lshl_add_u64 v[198:199], v[198:199], 0, s[10:11]
	s_mov_b64 exec, 0xffff
	global_store_dword v[198:199], v215, off
	s_mov_b64 exec, -1
	v_lshl_add_u64 v[198:199], v[198:199], 0, s[10:11]
	s_waitcnt vmcnt(28)
	v_cvt_pk_bf16_f32 v4, v144, v145
	v_cvt_pk_bf16_f32 v5, v146, v147
	v_cvt_pk_bf16_f32 v6, v148, v149
	v_cvt_pk_bf16_f32 v7, v150, v151
	v_cvt_pk_bf16_f32 v8, v152, v153
	v_cvt_pk_bf16_f32 v9, v154, v155
	v_cvt_pk_bf16_f32 v10, v156, v157
	v_cvt_pk_bf16_f32 v11, v158, v159
	global_store_dwordx4 v[196:197], v[4:7], off
	global_store_dwordx4 v[196:197], v[8:11], off offset:1024
	v_lshl_add_u64 v[196:197], v[196:197], 0, s[8:9]
	v_lshlrev_b32_e32 v144, 16, v4
	v_and_b32_e32 v145, 0xffff0000, v4
	v_lshlrev_b32_e32 v146, 16, v5
	v_and_b32_e32 v147, 0xffff0000, v5
	v_lshlrev_b32_e32 v148, 16, v6
	v_and_b32_e32 v149, 0xffff0000, v6
	v_lshlrev_b32_e32 v150, 16, v7
	v_and_b32_e32 v151, 0xffff0000, v7
	v_lshlrev_b32_e32 v152, 16, v8
	v_and_b32_e32 v153, 0xffff0000, v8
	v_lshlrev_b32_e32 v154, 16, v9
	v_and_b32_e32 v155, 0xffff0000, v9
	v_lshlrev_b32_e32 v156, 16, v10
	v_and_b32_e32 v157, 0xffff0000, v10
	v_lshlrev_b32_e32 v158, 16, v11
	v_and_b32_e32 v159, 0xffff0000, v11
	v_mul_f32_e32 v12, v145, v145
	v_fmac_f32_e32 v12, v144, v144
	v_fmac_f32_e32 v12, v146, v146
	v_fmac_f32_e32 v12, v147, v147
	v_fmac_f32_e32 v12, v148, v148
	v_fmac_f32_e32 v12, v149, v149
	v_fmac_f32_e32 v12, v150, v150
	v_fmac_f32_e32 v12, v151, v151
	v_fmac_f32_e32 v12, v152, v152
	v_fmac_f32_e32 v12, v153, v153
	v_fmac_f32_e32 v12, v154, v154
	v_fmac_f32_e32 v12, v155, v155
	v_fmac_f32_e32 v12, v156, v156
	v_fmac_f32_e32 v12, v157, v157
	v_fmac_f32_e32 v12, v158, v158
	v_fmac_f32_e32 v12, v159, v159
	s_waitcnt vmcnt(26)
	v_cvt_pk_bf16_f32 v206, v176, v177
	v_cvt_pk_bf16_f32 v207, v178, v179
	v_cvt_pk_bf16_f32 v208, v180, v181
	v_cvt_pk_bf16_f32 v209, v182, v183
	v_cvt_pk_bf16_f32 v210, v184, v185
	v_cvt_pk_bf16_f32 v211, v186, v187
	v_cvt_pk_bf16_f32 v212, v188, v189
	v_cvt_pk_bf16_f32 v213, v190, v191
	global_store_dwordx4 v[196:197], v[206:209], off
	global_store_dwordx4 v[196:197], v[210:213], off offset:1024
	v_lshl_add_u64 v[196:197], v[196:197], 0, s[8:9]
	v_lshlrev_b32_e32 v176, 16, v206
	v_and_b32_e32 v177, 0xffff0000, v206
	v_lshlrev_b32_e32 v178, 16, v207
	v_and_b32_e32 v179, 0xffff0000, v207
	v_lshlrev_b32_e32 v180, 16, v208
	v_and_b32_e32 v181, 0xffff0000, v208
	v_lshlrev_b32_e32 v182, 16, v209
	v_and_b32_e32 v183, 0xffff0000, v209
	v_lshlrev_b32_e32 v184, 16, v210
	v_and_b32_e32 v185, 0xffff0000, v210
	v_lshlrev_b32_e32 v186, 16, v211
	v_and_b32_e32 v187, 0xffff0000, v211
	v_lshlrev_b32_e32 v188, 16, v212
	v_and_b32_e32 v189, 0xffff0000, v212
	v_lshlrev_b32_e32 v190, 16, v213
	v_and_b32_e32 v191, 0xffff0000, v213
	v_mul_f32_e32 v214, v177, v177
	v_fmac_f32_e32 v214, v176, v176
	v_fmac_f32_e32 v214, v178, v178
	v_fmac_f32_e32 v214, v179, v179
	v_fmac_f32_e32 v214, v180, v180
	v_fmac_f32_e32 v214, v181, v181
	v_fmac_f32_e32 v214, v182, v182
	v_fmac_f32_e32 v214, v183, v183
	v_fmac_f32_e32 v214, v184, v184
	v_fmac_f32_e32 v214, v185, v185
	v_fmac_f32_e32 v214, v186, v186
	v_fmac_f32_e32 v214, v187, v187
	v_fmac_f32_e32 v214, v188, v188
	v_fmac_f32_e32 v214, v189, v189
	v_fmac_f32_e32 v214, v190, v190
	v_fmac_f32_e32 v214, v191, v191
	ds_bpermute_b32 v13, v200, v12
	ds_bpermute_b32 v215, v200, v214
	s_waitcnt lgkmcnt(0)
	v_add_f32_e32 v12, v12, v13
	v_add_f32_e32 v214, v214, v215
	ds_bpermute_b32 v13, v201, v12
	ds_bpermute_b32 v215, v201, v214
	s_waitcnt lgkmcnt(0)
	v_add_f32_e32 v12, v12, v13
	v_add_f32_e32 v214, v214, v215
	ds_bpermute_b32 v13, v202, v12
	ds_bpermute_b32 v215, v202, v214
	s_waitcnt lgkmcnt(0)
	v_add_f32_e32 v12, v12, v13
	v_add_f32_e32 v214, v214, v215
	ds_bpermute_b32 v13, v203, v12
	ds_bpermute_b32 v215, v203, v214
	s_waitcnt lgkmcnt(0)
	v_add_f32_e32 v12, v12, v13
	v_add_f32_e32 v214, v214, v215
	ds_bpermute_b32 v13, v204, v12
	ds_bpermute_b32 v215, v204, v214
	s_waitcnt lgkmcnt(0)
	v_add_f32_e32 v12, v12, v13
	v_add_f32_e32 v214, v214, v215
	ds_bpermute_b32 v13, v205, v12
	ds_bpermute_b32 v215, v205, v214
	s_waitcnt lgkmcnt(0)
	v_add_f32_e32 v12, v12, v13
	v_add_f32_e32 v214, v214, v215
	v_cndmask_b32_e64 v13, 0, v12, s[12:13]
	v_cndmask_b32_e64 v215, 0, v214, s[12:13]
	s_mov_b64 exec, 0xffff
	global_store_dword v[198:199], v13, off
	s_mov_b64 exec, -1
	v_lshl_add_u64 v[198:199], v[198:199], 0, s[10:11]
	s_mov_b64 exec, 0xffff
	global_store_dword v[198:199], v215, off
	s_mov_b64 exec, -1
	v_lshl_add_u64 v[198:199], v[198:199], 0, s[10:11]
	s_and_b64 vcc, exec, s[14:15]
	s_cbranch_vccz .Lxc_done
	s_waitcnt vmcnt(30)
	v_cvt_pk_bf16_f32 v4, v216, v217
	v_cvt_pk_bf16_f32 v5, v218, v219
	v_cvt_pk_bf16_f32 v6, v220, v221
	v_cvt_pk_bf16_f32 v7, v222, v223
	v_cvt_pk_bf16_f32 v8, v224, v225
	v_cvt_pk_bf16_f32 v9, v226, v227
	v_cvt_pk_bf16_f32 v10, v228, v229
	v_cvt_pk_bf16_f32 v11, v230, v231
	global_store_dwordx4 v[196:197], v[4:7], off
	global_store_dwordx4 v[196:197], v[8:11], off offset:1024
	v_lshl_add_u64 v[196:197], v[196:197], 0, s[8:9]
	v_lshlrev_b32_e32 v216, 16, v4
	v_and_b32_e32 v217, 0xffff0000, v4
	v_lshlrev_b32_e32 v218, 16, v5
	v_and_b32_e32 v219, 0xffff0000, v5
	v_lshlrev_b32_e32 v220, 16, v6
	v_and_b32_e32 v221, 0xffff0000, v6
	v_lshlrev_b32_e32 v222, 16, v7
	v_and_b32_e32 v223, 0xffff0000, v7
	v_lshlrev_b32_e32 v224, 16, v8
	v_and_b32_e32 v225, 0xffff0000, v8
	v_lshlrev_b32_e32 v226, 16, v9
	v_and_b32_e32 v227, 0xffff0000, v9
	v_lshlrev_b32_e32 v228, 16, v10
	v_and_b32_e32 v229, 0xffff0000, v10
	v_lshlrev_b32_e32 v230, 16, v11
	v_and_b32_e32 v231, 0xffff0000, v11
	v_mul_f32_e32 v12, v217, v217
	v_fmac_f32_e32 v12, v216, v216
	v_fmac_f32_e32 v12, v218, v218
	v_fmac_f32_e32 v12, v219, v219
	v_fmac_f32_e32 v12, v220, v220
	v_fmac_f32_e32 v12, v221, v221
	v_fmac_f32_e32 v12, v222, v222
	v_fmac_f32_e32 v12, v223, v223
	v_fmac_f32_e32 v12, v224, v224
	v_fmac_f32_e32 v12, v225, v225
	v_fmac_f32_e32 v12, v226, v226
	v_fmac_f32_e32 v12, v227, v227
	v_fmac_f32_e32 v12, v228, v228
	v_fmac_f32_e32 v12, v229, v229
	v_fmac_f32_e32 v12, v230, v230
	v_fmac_f32_e32 v12, v231, v231
	ds_bpermute_b32 v13, v200, v12
	s_waitcnt lgkmcnt(0)
	v_add_f32_e32 v12, v12, v13
	ds_bpermute_b32 v13, v201, v12
	s_waitcnt lgkmcnt(0)
	v_add_f32_e32 v12, v12, v13
	ds_bpermute_b32 v13, v202, v12
	s_waitcnt lgkmcnt(0)
	v_add_f32_e32 v12, v12, v13
	ds_bpermute_b32 v13, v203, v12
	s_waitcnt lgkmcnt(0)
	v_add_f32_e32 v12, v12, v13
	ds_bpermute_b32 v13, v204, v12
	s_waitcnt lgkmcnt(0)
	v_add_f32_e32 v12, v12, v13
	ds_bpermute_b32 v13, v205, v12
	s_waitcnt lgkmcnt(0)
	v_add_f32_e32 v12, v12, v13
	v_cndmask_b32_e64 v13, 0, v12, s[12:13]
	s_mov_b64 exec, 0xffff
	global_store_dword v[198:199], v13, off
	s_mov_b64 exec, -1
	v_lshl_add_u64 v[198:199], v[198:199], 0, s[10:11]
.Lxc_done:
	s_mov_b64 s[0:1], exec
	s_branch .LBB0_966
.Lxc_orig:
	v_readlane_b32 s0, v254, 0
	s_nop 1
	v_lshl_add_u32 v0, s0, 3, v9
	s_movk_i32 s0, 0x4000
	v_cmp_gt_i32_e32 vcc, s0, v0
	s_and_saveexec_b64 s[0:1], vcc
	s_cbranch_execz .LBB0_966
	v_mbcnt_lo_u32_b32 v1, -1, 0
	v_mbcnt_hi_u32_b32 v1, -1, v1
	v_readlane_b32 s2, v254, 40
	v_and_b32_e32 v3, 64, v1
	v_readlane_b32 s3, v254, 41
	s_add_u32 s6, s2, 0xb400000
	v_add_u32_e32 v11, 64, v3
	v_lshlrev_b32_e32 v4, 2, v8
	v_mov_b32_e32 v5, 0
	v_xor_b32_e32 v3, 32, v1
	s_addc_u32 s7, s3, 0
	v_lshl_add_u64 v[4:5], s[2:3], 0, v[4:5]
	s_mov_b64 s[2:3], 0xd400000
	v_cmp_lt_i32_e64 s[4:5], v3, v11
	v_xor_b32_e32 v7, 16, v1
	v_lshlrev_b32_e32 v2, 3, v8
	v_cmp_gt_u32_e32 vcc, 16, v8
	v_lshl_add_u64 v[4:5], v[4:5], 0, s[2:3]
	v_cmp_eq_u32_e64 s[2:3], 0, v8
	v_cndmask_b32_e64 v3, v1, v3, s[4:5]
	v_cmp_lt_i32_e64 s[4:5], v7, v11
	v_xor_b32_e32 v8, 8, v1
	v_xor_b32_e32 v9, 4, v1
	v_cndmask_b32_e64 v7, v1, v7, s[4:5]
	v_cmp_lt_i32_e64 s[4:5], v8, v11
	v_xor_b32_e32 v10, 2, v1
	v_xor_b32_e32 v12, 1, v1
	v_cndmask_b32_e64 v8, v1, v8, s[4:5]
	v_cmp_lt_i32_e64 s[4:5], v9, v11
	v_or_b32_e32 v6, 0x200, v2
	v_lshlrev_b32_e32 v3, 2, v3
	v_cndmask_b32_e64 v9, v1, v9, s[4:5]
	v_cmp_lt_i32_e64 s[4:5], v10, v11
	v_lshlrev_b32_e32 v7, 2, v7
	v_lshlrev_b32_e32 v8, 2, v8
	v_cndmask_b32_e64 v10, v1, v10, s[4:5]
	v_cmp_lt_i32_e64 s[4:5], v12, v11
	v_lshlrev_b32_e32 v9, 2, v9
	v_lshlrev_b32_e32 v10, 2, v10
	v_cndmask_b32_e64 v1, v1, v12, s[4:5]
	v_lshlrev_b32_e32 v11, 2, v1
	s_mov_b64 s[8:9], 0
	s_movk_i32 s10, 0x3fff
	s_branch .LBB0_964
